# PEER routing phase 3: the 8 per-head softmax row sums interleaved instruction by instruction (no hazard nops), same ops
# baseline (speedup 1.0000x reference)
.LBB0_1938:
	v_ashrrev_i32_e32 v103, 31, v102
	s_waitcnt vmcnt(5)
	v_lshrrev_b32_e32 v0, 19, v103
	v_add_u32_e32 v0, v102, v0
	v_ashrrev_i32_e32 v123, 13, v0
	v_readlane_b32 s0, v251, 44
	s_waitcnt vmcnt(0)
	v_lshlrev_b64 v[126:127], 10, v[102:103]
	v_lshl_add_u64 v[46:47], v[114:115], 0, v[126:127]
	v_add_u32_e32 v0, s0, v123
	s_movk_i32 s0, 0x1800
	v_mul_lo_u32 v16, v0, s0
	v_ashrrev_i32_e32 v17, 31, v16
	v_lshl_add_u64 v[128:129], v[16:17], 2, v[120:121]
	s_mov_b64 s[0:1], 0x4000
	v_lshl_add_u64 v[16:17], v[128:129], 0, s[0:1]
	s_mov_b64 s[0:1], 0x3000
	v_lshl_add_u64 v[18:19], v[128:129], 0, s[0:1]
	s_movk_i32 s0, 0x4000
	v_add_co_u32_e32 v28, vcc, s0, v128
	s_movk_i32 s0, 0x3000
	s_nop 0
	v_addc_co_u32_e32 v29, vcc, 0, v129, vcc
	v_lshlrev_b64 v[0:1], 12, v[102:103]
	v_add_co_u32_e32 v42, vcc, s0, v128
	v_lshl_add_u64 v[8:9], v[112:113], 0, v[0:1]
	s_nop 0
	v_addc_co_u32_e32 v43, vcc, 0, v129, vcc
	global_load_dwordx4 v[4:7], v[8:9], off offset:16
	global_load_dwordx4 v[0:3], v[8:9], off
	global_load_dwordx4 v[12:15], v[8:9], off offset:2064
	s_nop 0
	global_load_dwordx4 v[8:11], v[8:9], off offset:2048
	s_nop 0
	global_load_dwordx4 v[20:23], v[16:17], off offset:16
	global_load_dwordx4 v[24:27], v[18:19], off offset:16
	global_load_dwordx4 v[34:37], v[28:29], off
	s_nop 0
	global_load_dwordx4 v[28:31], v[28:29], off offset:2048
	s_nop 0
	global_load_dwordx4 v[38:41], v[42:43], off
	s_nop 0
	global_load_dwordx4 v[42:45], v[42:43], off offset:2048
	s_mov_b64 s[0:1], 0x4800
	v_lshl_add_u64 v[16:17], v[128:129], 0, s[0:1]
	s_mov_b64 s[0:1], 0x3800
	v_lshl_add_u64 v[18:19], v[128:129], 0, s[0:1]
	global_load_dwordx4 v[50:53], v[46:47], off
	s_nop 0
	global_load_dwordx4 v[46:49], v[16:17], off offset:16
	s_nop 0
	global_load_dwordx4 v[16:19], v[18:19], off offset:16
	v_writelane_b32 v253, s2, 26
	s_mov_b64 s[0:1], 0x800
	s_mov_b32 s14, 0
	v_writelane_b32 v253, s3, 27
	v_lshl_add_u64 v[130:131], v[128:129], 0, s[0:1]
	v_mov_b32_e32 v54, v174
	s_waitcnt vmcnt(2)
	ds_write_b128 v176, v[50:53]
	v_readfirstlane_b32 s0, v206
	s_lshr_b32 s0, s0, 6
	s_lshl_b32 s1, s0, 10
	s_add_u32 s1, s1, 0x2000
	s_lshl_b32 s2, s0, 12
	s_add_u32 s2, s2, 0x4000
	v_and_b32_e32 v55, 0xff, v178
	v_and_b32_e32 v56, 0xff, v179
	v_add_u32_e32 v55, s1, v55
	v_add_u32_e32 v56, s1, v56
	v_lshl_add_u32 v57, v214, 2, s2
	v_mov_b32_e32 v58, s2
	v_sub_u32_e32 v59, 63, v214
	v_lshl_add_u32 v101, v214, 3, s2
	v_add_u32_e32 v101, 0x800, v101
	s_mov_b32 s34, -1
	s_mov_b32 s35, 0x3ffff
	s_mov_b32 s36, 0xffffffc0
	ds_read_b32 v88, v55 offset:0
	ds_read_b32 v80, v56 offset:0
	ds_read_b32 v89, v55 offset:128
	ds_read_b32 v81, v56 offset:128
	ds_read_b32 v90, v55 offset:256
	ds_read_b32 v82, v56 offset:256
	ds_read_b32 v91, v55 offset:384
	ds_read_b32 v83, v56 offset:384
	ds_read_b32 v92, v55 offset:512
	ds_read_b32 v84, v56 offset:512
	ds_read_b32 v93, v55 offset:640
	ds_read_b32 v85, v56 offset:640
	ds_read_b32 v94, v55 offset:768
	ds_read_b32 v86, v56 offset:768
	ds_read_b32 v95, v55 offset:896
	ds_read_b32 v87, v56 offset:896
	s_waitcnt lgkmcnt(0)
	v_and_b32_e32 v61, 0xffffff80, v88
	v_and_b32_e32 v62, 0xffffff80, v80
	v_add_f32_e32 v64, v61, v62
	v_and_b32_e32 v61, 0x7f, v88
	v_and_b32_e32 v62, 0x7f, v80
	v_cndmask_b32_e64 v64, v222, v64, s[34:35]
	v_lshl_or_b32 v61, v61, 7, v62
	v_sub_u32_e32 v80, 0x3fff, v61
	v_ashrrev_i32_e32 v62, 31, v64
	v_or_b32_e32 v62, 0x80000000, v62
	v_xor_b32_e32 v62, v64, v62
	v_and_or_b32 v72, v62, s36, v59
	ds_write_b32 v57, v72 offset:0
	v_mov_b32_e32 v88, 0
	v_and_b32_e32 v61, 0xffffff80, v89
	v_and_b32_e32 v62, 0xffffff80, v81
	v_add_f32_e32 v65, v61, v62
	v_and_b32_e32 v61, 0x7f, v89
	v_and_b32_e32 v62, 0x7f, v81
	v_cndmask_b32_e64 v65, v222, v65, s[34:35]
	v_lshl_or_b32 v61, v61, 7, v62
	v_sub_u32_e32 v81, 0x3fff, v61
	v_ashrrev_i32_e32 v62, 31, v65
	v_or_b32_e32 v62, 0x80000000, v62
	v_xor_b32_e32 v62, v65, v62
	v_and_or_b32 v73, v62, s36, v59
	ds_write_b32 v57, v73 offset:256
	v_mov_b32_e32 v89, 0
	v_and_b32_e32 v61, 0xffffff80, v90
	v_and_b32_e32 v62, 0xffffff80, v82
	v_add_f32_e32 v66, v61, v62
	v_and_b32_e32 v61, 0x7f, v90
	v_and_b32_e32 v62, 0x7f, v82
	v_cndmask_b32_e64 v66, v222, v66, s[34:35]
	v_lshl_or_b32 v61, v61, 7, v62
	v_sub_u32_e32 v82, 0x3fff, v61
	v_ashrrev_i32_e32 v62, 31, v66
	v_or_b32_e32 v62, 0x80000000, v62
	v_xor_b32_e32 v62, v66, v62
	v_and_or_b32 v74, v62, s36, v59
	ds_write_b32 v57, v74 offset:512
	v_mov_b32_e32 v90, 0
	v_and_b32_e32 v61, 0xffffff80, v91
	v_and_b32_e32 v62, 0xffffff80, v83
	v_add_f32_e32 v67, v61, v62
	v_and_b32_e32 v61, 0x7f, v91
	v_and_b32_e32 v62, 0x7f, v83
	v_cndmask_b32_e64 v67, v222, v67, s[34:35]
	v_lshl_or_b32 v61, v61, 7, v62
	v_sub_u32_e32 v83, 0x3fff, v61
	v_ashrrev_i32_e32 v62, 31, v67
	v_or_b32_e32 v62, 0x80000000, v62
	v_xor_b32_e32 v62, v67, v62
	v_and_or_b32 v75, v62, s36, v59
	ds_write_b32 v57, v75 offset:768
	v_mov_b32_e32 v91, 0
	v_and_b32_e32 v61, 0xffffff80, v92
	v_and_b32_e32 v62, 0xffffff80, v84
	v_add_f32_e32 v68, v61, v62
	v_and_b32_e32 v61, 0x7f, v92
	v_and_b32_e32 v62, 0x7f, v84
	v_cndmask_b32_e64 v68, v222, v68, s[34:35]
	v_lshl_or_b32 v61, v61, 7, v62
	v_sub_u32_e32 v84, 0x3fff, v61
	v_ashrrev_i32_e32 v62, 31, v68
	v_or_b32_e32 v62, 0x80000000, v62
	v_xor_b32_e32 v62, v68, v62
	v_and_or_b32 v76, v62, s36, v59
	ds_write_b32 v57, v76 offset:1024
	v_mov_b32_e32 v92, 0
	v_and_b32_e32 v61, 0xffffff80, v93
	v_and_b32_e32 v62, 0xffffff80, v85
	v_add_f32_e32 v69, v61, v62
	v_and_b32_e32 v61, 0x7f, v93
	v_and_b32_e32 v62, 0x7f, v85
	v_cndmask_b32_e64 v69, v222, v69, s[34:35]
	v_lshl_or_b32 v61, v61, 7, v62
	v_sub_u32_e32 v85, 0x3fff, v61
	v_ashrrev_i32_e32 v62, 31, v69
	v_or_b32_e32 v62, 0x80000000, v62
	v_xor_b32_e32 v62, v69, v62
	v_and_or_b32 v77, v62, s36, v59
	ds_write_b32 v57, v77 offset:1280
	v_mov_b32_e32 v93, 0
	v_and_b32_e32 v61, 0xffffff80, v94
	v_and_b32_e32 v62, 0xffffff80, v86
	v_add_f32_e32 v70, v61, v62
	v_and_b32_e32 v61, 0x7f, v94
	v_and_b32_e32 v62, 0x7f, v86
	v_cndmask_b32_e64 v70, v222, v70, s[34:35]
	v_lshl_or_b32 v61, v61, 7, v62
	v_sub_u32_e32 v86, 0x3fff, v61
	v_ashrrev_i32_e32 v62, 31, v70
	v_or_b32_e32 v62, 0x80000000, v62
	v_xor_b32_e32 v62, v70, v62
	v_and_or_b32 v78, v62, s36, v59
	ds_write_b32 v57, v78 offset:1536
	v_mov_b32_e32 v94, 0
	v_and_b32_e32 v61, 0xffffff80, v95
	v_and_b32_e32 v62, 0xffffff80, v87
	v_add_f32_e32 v71, v61, v62
	v_and_b32_e32 v61, 0x7f, v95
	v_and_b32_e32 v62, 0x7f, v87
	v_cndmask_b32_e64 v71, v222, v71, s[34:35]
	v_lshl_or_b32 v61, v61, 7, v62
	v_sub_u32_e32 v87, 0x3fff, v61
	v_ashrrev_i32_e32 v62, 31, v71
	v_or_b32_e32 v62, 0x80000000, v62
	v_xor_b32_e32 v62, v71, v62
	v_and_or_b32 v79, v62, s36, v59
	ds_write_b32 v57, v79 offset:1792
	v_mov_b32_e32 v95, 0
	ds_read_b128 v[96:99], v58 offset:0
	ds_read_b128 v[60:63], v58 offset:16
	s_waitcnt lgkmcnt(1)
	v_cmp_gt_u32_e64 s[20:21], v96, v72
	v_cmp_gt_u32_e64 s[22:23], v97, v72
	v_cmp_gt_u32_e64 s[24:25], v98, v72
	v_addc_co_u32_e64 v88, s[30:31], 0, v88, s[20:21]
	v_cmp_gt_u32_e64 s[26:27], v99, v72
	v_addc_co_u32_e64 v88, s[30:31], 0, v88, s[22:23]
	ds_read_b128 v[96:99], v58 offset:32
	s_waitcnt lgkmcnt(1)
	v_cmp_gt_u32_e64 s[20:21], v60, v72
	v_addc_co_u32_e64 v88, s[30:31], 0, v88, s[24:25]
	v_cmp_gt_u32_e64 s[22:23], v61, v72
	v_addc_co_u32_e64 v88, s[30:31], 0, v88, s[26:27]
	v_cmp_gt_u32_e64 s[24:25], v62, v72
	v_addc_co_u32_e64 v88, s[30:31], 0, v88, s[20:21]
	v_cmp_gt_u32_e64 s[26:27], v63, v72
	v_addc_co_u32_e64 v88, s[30:31], 0, v88, s[22:23]
	ds_read_b128 v[60:63], v58 offset:48
	s_waitcnt lgkmcnt(1)
	v_cmp_gt_u32_e64 s[20:21], v96, v72
	v_addc_co_u32_e64 v88, s[30:31], 0, v88, s[24:25]
	v_cmp_gt_u32_e64 s[22:23], v97, v72
	v_addc_co_u32_e64 v88, s[30:31], 0, v88, s[26:27]
	v_cmp_gt_u32_e64 s[24:25], v98, v72
	v_addc_co_u32_e64 v88, s[30:31], 0, v88, s[20:21]
	v_cmp_gt_u32_e64 s[26:27], v99, v72
	v_addc_co_u32_e64 v88, s[30:31], 0, v88, s[22:23]
	ds_read_b128 v[96:99], v58 offset:64
	s_waitcnt lgkmcnt(1)
	v_cmp_gt_u32_e64 s[20:21], v60, v72
	v_addc_co_u32_e64 v88, s[30:31], 0, v88, s[24:25]
	v_cmp_gt_u32_e64 s[22:23], v61, v72
	v_addc_co_u32_e64 v88, s[30:31], 0, v88, s[26:27]
	v_cmp_gt_u32_e64 s[24:25], v62, v72
	v_addc_co_u32_e64 v88, s[30:31], 0, v88, s[20:21]
	v_cmp_gt_u32_e64 s[26:27], v63, v72
	v_addc_co_u32_e64 v88, s[30:31], 0, v88, s[22:23]
	ds_read_b128 v[60:63], v58 offset:80
	s_waitcnt lgkmcnt(1)
	v_cmp_gt_u32_e64 s[20:21], v96, v72
	v_addc_co_u32_e64 v88, s[30:31], 0, v88, s[24:25]
	v_cmp_gt_u32_e64 s[22:23], v97, v72
	v_addc_co_u32_e64 v88, s[30:31], 0, v88, s[26:27]
	v_cmp_gt_u32_e64 s[24:25], v98, v72
	v_addc_co_u32_e64 v88, s[30:31], 0, v88, s[20:21]
	v_cmp_gt_u32_e64 s[26:27], v99, v72
	v_addc_co_u32_e64 v88, s[30:31], 0, v88, s[22:23]
	ds_read_b128 v[96:99], v58 offset:96
	s_waitcnt lgkmcnt(1)
	v_cmp_gt_u32_e64 s[20:21], v60, v72
	v_addc_co_u32_e64 v88, s[30:31], 0, v88, s[24:25]
	v_cmp_gt_u32_e64 s[22:23], v61, v72
	v_addc_co_u32_e64 v88, s[30:31], 0, v88, s[26:27]
	v_cmp_gt_u32_e64 s[24:25], v62, v72
	v_addc_co_u32_e64 v88, s[30:31], 0, v88, s[20:21]
	v_cmp_gt_u32_e64 s[26:27], v63, v72
	v_addc_co_u32_e64 v88, s[30:31], 0, v88, s[22:23]
	ds_read_b128 v[60:63], v58 offset:112
	s_waitcnt lgkmcnt(1)
	v_cmp_gt_u32_e64 s[20:21], v96, v72
	v_addc_co_u32_e64 v88, s[30:31], 0, v88, s[24:25]
	v_cmp_gt_u32_e64 s[22:23], v97, v72
	v_addc_co_u32_e64 v88, s[30:31], 0, v88, s[26:27]
	v_cmp_gt_u32_e64 s[24:25], v98, v72
	v_addc_co_u32_e64 v88, s[30:31], 0, v88, s[20:21]
	v_cmp_gt_u32_e64 s[26:27], v99, v72
	v_addc_co_u32_e64 v88, s[30:31], 0, v88, s[22:23]
	ds_read_b128 v[96:99], v58 offset:128
	s_waitcnt lgkmcnt(1)
	v_cmp_gt_u32_e64 s[20:21], v60, v72
	v_addc_co_u32_e64 v88, s[30:31], 0, v88, s[24:25]
	v_cmp_gt_u32_e64 s[22:23], v61, v72
	v_addc_co_u32_e64 v88, s[30:31], 0, v88, s[26:27]
	v_cmp_gt_u32_e64 s[24:25], v62, v72
	v_addc_co_u32_e64 v88, s[30:31], 0, v88, s[20:21]
	v_cmp_gt_u32_e64 s[26:27], v63, v72
	v_addc_co_u32_e64 v88, s[30:31], 0, v88, s[22:23]
	ds_read_b128 v[60:63], v58 offset:144
	s_waitcnt lgkmcnt(1)
	v_cmp_gt_u32_e64 s[20:21], v96, v72
	v_addc_co_u32_e64 v88, s[30:31], 0, v88, s[24:25]
	v_cmp_gt_u32_e64 s[22:23], v97, v72
	v_addc_co_u32_e64 v88, s[30:31], 0, v88, s[26:27]
	v_cmp_gt_u32_e64 s[24:25], v98, v72
	v_addc_co_u32_e64 v88, s[30:31], 0, v88, s[20:21]
	v_cmp_gt_u32_e64 s[26:27], v99, v72
	v_addc_co_u32_e64 v88, s[30:31], 0, v88, s[22:23]
	ds_read_b128 v[96:99], v58 offset:160
	s_waitcnt lgkmcnt(1)
	v_cmp_gt_u32_e64 s[20:21], v60, v72
	v_addc_co_u32_e64 v88, s[30:31], 0, v88, s[24:25]
	v_cmp_gt_u32_e64 s[22:23], v61, v72
	v_addc_co_u32_e64 v88, s[30:31], 0, v88, s[26:27]
	v_cmp_gt_u32_e64 s[24:25], v62, v72
	v_addc_co_u32_e64 v88, s[30:31], 0, v88, s[20:21]
	v_cmp_gt_u32_e64 s[26:27], v63, v72
	v_addc_co_u32_e64 v88, s[30:31], 0, v88, s[22:23]
	ds_read_b128 v[60:63], v58 offset:176
	s_waitcnt lgkmcnt(1)
	v_cmp_gt_u32_e64 s[20:21], v96, v72
	v_addc_co_u32_e64 v88, s[30:31], 0, v88, s[24:25]
	v_cmp_gt_u32_e64 s[22:23], v97, v72
	v_addc_co_u32_e64 v88, s[30:31], 0, v88, s[26:27]
	v_cmp_gt_u32_e64 s[24:25], v98, v72
	v_addc_co_u32_e64 v88, s[30:31], 0, v88, s[20:21]
	v_cmp_gt_u32_e64 s[26:27], v99, v72
	v_addc_co_u32_e64 v88, s[30:31], 0, v88, s[22:23]
	ds_read_b128 v[96:99], v58 offset:192
	s_waitcnt lgkmcnt(1)
	v_cmp_gt_u32_e64 s[20:21], v60, v72
	v_addc_co_u32_e64 v88, s[30:31], 0, v88, s[24:25]
	v_cmp_gt_u32_e64 s[22:23], v61, v72
	v_addc_co_u32_e64 v88, s[30:31], 0, v88, s[26:27]
	v_cmp_gt_u32_e64 s[24:25], v62, v72
	v_addc_co_u32_e64 v88, s[30:31], 0, v88, s[20:21]
	v_cmp_gt_u32_e64 s[26:27], v63, v72
	v_addc_co_u32_e64 v88, s[30:31], 0, v88, s[22:23]
	s_waitcnt lgkmcnt(0)
	v_cmp_gt_u32_e64 s[20:21], v96, v72
	v_addc_co_u32_e64 v88, s[30:31], 0, v88, s[24:25]
	v_cmp_gt_u32_e64 s[22:23], v97, v72
	v_addc_co_u32_e64 v88, s[30:31], 0, v88, s[26:27]
	v_addc_co_u32_e64 v88, s[30:31], 0, v88, s[20:21]
	s_nop 1
	v_addc_co_u32_e64 v88, s[30:31], 0, v88, s[22:23]
	ds_read_b128 v[96:99], v58 offset:256
	ds_read_b128 v[60:63], v58 offset:272
	s_waitcnt lgkmcnt(1)
	v_cmp_gt_u32_e64 s[20:21], v96, v73
	v_cmp_gt_u32_e64 s[22:23], v97, v73
	v_cmp_gt_u32_e64 s[24:25], v98, v73
	v_addc_co_u32_e64 v89, s[30:31], 0, v89, s[20:21]
	v_cmp_gt_u32_e64 s[26:27], v99, v73
	v_addc_co_u32_e64 v89, s[30:31], 0, v89, s[22:23]
	ds_read_b128 v[96:99], v58 offset:288
	s_waitcnt lgkmcnt(1)
	v_cmp_gt_u32_e64 s[20:21], v60, v73
	v_addc_co_u32_e64 v89, s[30:31], 0, v89, s[24:25]
	v_cmp_gt_u32_e64 s[22:23], v61, v73
	v_addc_co_u32_e64 v89, s[30:31], 0, v89, s[26:27]
	v_cmp_gt_u32_e64 s[24:25], v62, v73
	v_addc_co_u32_e64 v89, s[30:31], 0, v89, s[20:21]
	v_cmp_gt_u32_e64 s[26:27], v63, v73
	v_addc_co_u32_e64 v89, s[30:31], 0, v89, s[22:23]
	ds_read_b128 v[60:63], v58 offset:304
	s_waitcnt lgkmcnt(1)
	v_cmp_gt_u32_e64 s[20:21], v96, v73
	v_addc_co_u32_e64 v89, s[30:31], 0, v89, s[24:25]
	v_cmp_gt_u32_e64 s[22:23], v97, v73
	v_addc_co_u32_e64 v89, s[30:31], 0, v89, s[26:27]
	v_cmp_gt_u32_e64 s[24:25], v98, v73
	v_addc_co_u32_e64 v89, s[30:31], 0, v89, s[20:21]
	v_cmp_gt_u32_e64 s[26:27], v99, v73
	v_addc_co_u32_e64 v89, s[30:31], 0, v89, s[22:23]
	ds_read_b128 v[96:99], v58 offset:320
	s_waitcnt lgkmcnt(1)
	v_cmp_gt_u32_e64 s[20:21], v60, v73
	v_addc_co_u32_e64 v89, s[30:31], 0, v89, s[24:25]
	v_cmp_gt_u32_e64 s[22:23], v61, v73
	v_addc_co_u32_e64 v89, s[30:31], 0, v89, s[26:27]
	v_cmp_gt_u32_e64 s[24:25], v62, v73
	v_addc_co_u32_e64 v89, s[30:31], 0, v89, s[20:21]
	v_cmp_gt_u32_e64 s[26:27], v63, v73
	v_addc_co_u32_e64 v89, s[30:31], 0, v89, s[22:23]
	ds_read_b128 v[60:63], v58 offset:336
	s_waitcnt lgkmcnt(1)
	v_cmp_gt_u32_e64 s[20:21], v96, v73
	v_addc_co_u32_e64 v89, s[30:31], 0, v89, s[24:25]
	v_cmp_gt_u32_e64 s[22:23], v97, v73
	v_addc_co_u32_e64 v89, s[30:31], 0, v89, s[26:27]
	v_cmp_gt_u32_e64 s[24:25], v98, v73
	v_addc_co_u32_e64 v89, s[30:31], 0, v89, s[20:21]
	v_cmp_gt_u32_e64 s[26:27], v99, v73
	v_addc_co_u32_e64 v89, s[30:31], 0, v89, s[22:23]
	ds_read_b128 v[96:99], v58 offset:352
	s_waitcnt lgkmcnt(1)
	v_cmp_gt_u32_e64 s[20:21], v60, v73
	v_addc_co_u32_e64 v89, s[30:31], 0, v89, s[24:25]
	v_cmp_gt_u32_e64 s[22:23], v61, v73
	v_addc_co_u32_e64 v89, s[30:31], 0, v89, s[26:27]
	v_cmp_gt_u32_e64 s[24:25], v62, v73
	v_addc_co_u32_e64 v89, s[30:31], 0, v89, s[20:21]
	v_cmp_gt_u32_e64 s[26:27], v63, v73
	v_addc_co_u32_e64 v89, s[30:31], 0, v89, s[22:23]
	ds_read_b128 v[60:63], v58 offset:368
	s_waitcnt lgkmcnt(1)
	v_cmp_gt_u32_e64 s[20:21], v96, v73
	v_addc_co_u32_e64 v89, s[30:31], 0, v89, s[24:25]
	v_cmp_gt_u32_e64 s[22:23], v97, v73
	v_addc_co_u32_e64 v89, s[30:31], 0, v89, s[26:27]
	v_cmp_gt_u32_e64 s[24:25], v98, v73
	v_addc_co_u32_e64 v89, s[30:31], 0, v89, s[20:21]
	v_cmp_gt_u32_e64 s[26:27], v99, v73
	v_addc_co_u32_e64 v89, s[30:31], 0, v89, s[22:23]
	ds_read_b128 v[96:99], v58 offset:384
	s_waitcnt lgkmcnt(1)
	v_cmp_gt_u32_e64 s[20:21], v60, v73
	v_addc_co_u32_e64 v89, s[30:31], 0, v89, s[24:25]
	v_cmp_gt_u32_e64 s[22:23], v61, v73
	v_addc_co_u32_e64 v89, s[30:31], 0, v89, s[26:27]
	v_cmp_gt_u32_e64 s[24:25], v62, v73
	v_addc_co_u32_e64 v89, s[30:31], 0, v89, s[20:21]
	v_cmp_gt_u32_e64 s[26:27], v63, v73
	v_addc_co_u32_e64 v89, s[30:31], 0, v89, s[22:23]
	ds_read_b128 v[60:63], v58 offset:400
	s_waitcnt lgkmcnt(1)
	v_cmp_gt_u32_e64 s[20:21], v96, v73
	v_addc_co_u32_e64 v89, s[30:31], 0, v89, s[24:25]
	v_cmp_gt_u32_e64 s[22:23], v97, v73
	v_addc_co_u32_e64 v89, s[30:31], 0, v89, s[26:27]
	v_cmp_gt_u32_e64 s[24:25], v98, v73
	v_addc_co_u32_e64 v89, s[30:31], 0, v89, s[20:21]
	v_cmp_gt_u32_e64 s[26:27], v99, v73
	v_addc_co_u32_e64 v89, s[30:31], 0, v89, s[22:23]
	ds_read_b128 v[96:99], v58 offset:416
	s_waitcnt lgkmcnt(1)
	v_cmp_gt_u32_e64 s[20:21], v60, v73
	v_addc_co_u32_e64 v89, s[30:31], 0, v89, s[24:25]
	v_cmp_gt_u32_e64 s[22:23], v61, v73
	v_addc_co_u32_e64 v89, s[30:31], 0, v89, s[26:27]
	v_cmp_gt_u32_e64 s[24:25], v62, v73
	v_addc_co_u32_e64 v89, s[30:31], 0, v89, s[20:21]
	v_cmp_gt_u32_e64 s[26:27], v63, v73
	v_addc_co_u32_e64 v89, s[30:31], 0, v89, s[22:23]
	ds_read_b128 v[60:63], v58 offset:432
	s_waitcnt lgkmcnt(1)
	v_cmp_gt_u32_e64 s[20:21], v96, v73
	v_addc_co_u32_e64 v89, s[30:31], 0, v89, s[24:25]
	v_cmp_gt_u32_e64 s[22:23], v97, v73
	v_addc_co_u32_e64 v89, s[30:31], 0, v89, s[26:27]
	v_cmp_gt_u32_e64 s[24:25], v98, v73
	v_addc_co_u32_e64 v89, s[30:31], 0, v89, s[20:21]
	v_cmp_gt_u32_e64 s[26:27], v99, v73
	v_addc_co_u32_e64 v89, s[30:31], 0, v89, s[22:23]
	ds_read_b128 v[96:99], v58 offset:448
	s_waitcnt lgkmcnt(1)
	v_cmp_gt_u32_e64 s[20:21], v60, v73
	v_addc_co_u32_e64 v89, s[30:31], 0, v89, s[24:25]
	v_cmp_gt_u32_e64 s[22:23], v61, v73
	v_addc_co_u32_e64 v89, s[30:31], 0, v89, s[26:27]
	v_cmp_gt_u32_e64 s[24:25], v62, v73
	v_addc_co_u32_e64 v89, s[30:31], 0, v89, s[20:21]
	v_cmp_gt_u32_e64 s[26:27], v63, v73
	v_addc_co_u32_e64 v89, s[30:31], 0, v89, s[22:23]
	s_waitcnt lgkmcnt(0)
	v_cmp_gt_u32_e64 s[20:21], v96, v73
	v_addc_co_u32_e64 v89, s[30:31], 0, v89, s[24:25]
	v_cmp_gt_u32_e64 s[22:23], v97, v73
	v_addc_co_u32_e64 v89, s[30:31], 0, v89, s[26:27]
	v_addc_co_u32_e64 v89, s[30:31], 0, v89, s[20:21]
	s_nop 1
	v_addc_co_u32_e64 v89, s[30:31], 0, v89, s[22:23]
	ds_read_b128 v[96:99], v58 offset:512
	ds_read_b128 v[60:63], v58 offset:528
	s_waitcnt lgkmcnt(1)
	v_cmp_gt_u32_e64 s[20:21], v96, v74
	v_cmp_gt_u32_e64 s[22:23], v97, v74
	v_cmp_gt_u32_e64 s[24:25], v98, v74
	v_addc_co_u32_e64 v90, s[30:31], 0, v90, s[20:21]
	v_cmp_gt_u32_e64 s[26:27], v99, v74
	v_addc_co_u32_e64 v90, s[30:31], 0, v90, s[22:23]
	ds_read_b128 v[96:99], v58 offset:544
	s_waitcnt lgkmcnt(1)
	v_cmp_gt_u32_e64 s[20:21], v60, v74
	v_addc_co_u32_e64 v90, s[30:31], 0, v90, s[24:25]
	v_cmp_gt_u32_e64 s[22:23], v61, v74
	v_addc_co_u32_e64 v90, s[30:31], 0, v90, s[26:27]
	v_cmp_gt_u32_e64 s[24:25], v62, v74
	v_addc_co_u32_e64 v90, s[30:31], 0, v90, s[20:21]
	v_cmp_gt_u32_e64 s[26:27], v63, v74
	v_addc_co_u32_e64 v90, s[30:31], 0, v90, s[22:23]
	ds_read_b128 v[60:63], v58 offset:560
	s_waitcnt lgkmcnt(1)
	v_cmp_gt_u32_e64 s[20:21], v96, v74
	v_addc_co_u32_e64 v90, s[30:31], 0, v90, s[24:25]
	v_cmp_gt_u32_e64 s[22:23], v97, v74
	v_addc_co_u32_e64 v90, s[30:31], 0, v90, s[26:27]
	v_cmp_gt_u32_e64 s[24:25], v98, v74
	v_addc_co_u32_e64 v90, s[30:31], 0, v90, s[20:21]
	v_cmp_gt_u32_e64 s[26:27], v99, v74
	v_addc_co_u32_e64 v90, s[30:31], 0, v90, s[22:23]
	ds_read_b128 v[96:99], v58 offset:576
	s_waitcnt lgkmcnt(1)
	v_cmp_gt_u32_e64 s[20:21], v60, v74
	v_addc_co_u32_e64 v90, s[30:31], 0, v90, s[24:25]
	v_cmp_gt_u32_e64 s[22:23], v61, v74
	v_addc_co_u32_e64 v90, s[30:31], 0, v90, s[26:27]
	v_cmp_gt_u32_e64 s[24:25], v62, v74
	v_addc_co_u32_e64 v90, s[30:31], 0, v90, s[20:21]
	v_cmp_gt_u32_e64 s[26:27], v63, v74
	v_addc_co_u32_e64 v90, s[30:31], 0, v90, s[22:23]
	ds_read_b128 v[60:63], v58 offset:592
	s_waitcnt lgkmcnt(1)
	v_cmp_gt_u32_e64 s[20:21], v96, v74
	v_addc_co_u32_e64 v90, s[30:31], 0, v90, s[24:25]
	v_cmp_gt_u32_e64 s[22:23], v97, v74
	v_addc_co_u32_e64 v90, s[30:31], 0, v90, s[26:27]
	v_cmp_gt_u32_e64 s[24:25], v98, v74
	v_addc_co_u32_e64 v90, s[30:31], 0, v90, s[20:21]
	v_cmp_gt_u32_e64 s[26:27], v99, v74
	v_addc_co_u32_e64 v90, s[30:31], 0, v90, s[22:23]
	ds_read_b128 v[96:99], v58 offset:608
	s_waitcnt lgkmcnt(1)
	v_cmp_gt_u32_e64 s[20:21], v60, v74
	v_addc_co_u32_e64 v90, s[30:31], 0, v90, s[24:25]
	v_cmp_gt_u32_e64 s[22:23], v61, v74
	v_addc_co_u32_e64 v90, s[30:31], 0, v90, s[26:27]
	v_cmp_gt_u32_e64 s[24:25], v62, v74
	v_addc_co_u32_e64 v90, s[30:31], 0, v90, s[20:21]
	v_cmp_gt_u32_e64 s[26:27], v63, v74
	v_addc_co_u32_e64 v90, s[30:31], 0, v90, s[22:23]
	ds_read_b128 v[60:63], v58 offset:624
	s_waitcnt lgkmcnt(1)
	v_cmp_gt_u32_e64 s[20:21], v96, v74
	v_addc_co_u32_e64 v90, s[30:31], 0, v90, s[24:25]
	v_cmp_gt_u32_e64 s[22:23], v97, v74
	v_addc_co_u32_e64 v90, s[30:31], 0, v90, s[26:27]
	v_cmp_gt_u32_e64 s[24:25], v98, v74
	v_addc_co_u32_e64 v90, s[30:31], 0, v90, s[20:21]
	v_cmp_gt_u32_e64 s[26:27], v99, v74
	v_addc_co_u32_e64 v90, s[30:31], 0, v90, s[22:23]
	ds_read_b128 v[96:99], v58 offset:640
	s_waitcnt lgkmcnt(1)
	v_cmp_gt_u32_e64 s[20:21], v60, v74
	v_addc_co_u32_e64 v90, s[30:31], 0, v90, s[24:25]
	v_cmp_gt_u32_e64 s[22:23], v61, v74
	v_addc_co_u32_e64 v90, s[30:31], 0, v90, s[26:27]
	v_cmp_gt_u32_e64 s[24:25], v62, v74
	v_addc_co_u32_e64 v90, s[30:31], 0, v90, s[20:21]
	v_cmp_gt_u32_e64 s[26:27], v63, v74
	v_addc_co_u32_e64 v90, s[30:31], 0, v90, s[22:23]
	ds_read_b128 v[60:63], v58 offset:656
	s_waitcnt lgkmcnt(1)
	v_cmp_gt_u32_e64 s[20:21], v96, v74
	v_addc_co_u32_e64 v90, s[30:31], 0, v90, s[24:25]
	v_cmp_gt_u32_e64 s[22:23], v97, v74
	v_addc_co_u32_e64 v90, s[30:31], 0, v90, s[26:27]
	v_cmp_gt_u32_e64 s[24:25], v98, v74
	v_addc_co_u32_e64 v90, s[30:31], 0, v90, s[20:21]
	v_cmp_gt_u32_e64 s[26:27], v99, v74
	v_addc_co_u32_e64 v90, s[30:31], 0, v90, s[22:23]
	ds_read_b128 v[96:99], v58 offset:672
	s_waitcnt lgkmcnt(1)
	v_cmp_gt_u32_e64 s[20:21], v60, v74
	v_addc_co_u32_e64 v90, s[30:31], 0, v90, s[24:25]
	v_cmp_gt_u32_e64 s[22:23], v61, v74
	v_addc_co_u32_e64 v90, s[30:31], 0, v90, s[26:27]
	v_cmp_gt_u32_e64 s[24:25], v62, v74
	v_addc_co_u32_e64 v90, s[30:31], 0, v90, s[20:21]
	v_cmp_gt_u32_e64 s[26:27], v63, v74
	v_addc_co_u32_e64 v90, s[30:31], 0, v90, s[22:23]
	ds_read_b128 v[60:63], v58 offset:688
	s_waitcnt lgkmcnt(1)
	v_cmp_gt_u32_e64 s[20:21], v96, v74
	v_addc_co_u32_e64 v90, s[30:31], 0, v90, s[24:25]
	v_cmp_gt_u32_e64 s[22:23], v97, v74
	v_addc_co_u32_e64 v90, s[30:31], 0, v90, s[26:27]
	v_cmp_gt_u32_e64 s[24:25], v98, v74
	v_addc_co_u32_e64 v90, s[30:31], 0, v90, s[20:21]
	v_cmp_gt_u32_e64 s[26:27], v99, v74
	v_addc_co_u32_e64 v90, s[30:31], 0, v90, s[22:23]
	ds_read_b128 v[96:99], v58 offset:704
	s_waitcnt lgkmcnt(1)
	v_cmp_gt_u32_e64 s[20:21], v60, v74
	v_addc_co_u32_e64 v90, s[30:31], 0, v90, s[24:25]
	v_cmp_gt_u32_e64 s[22:23], v61, v74
	v_addc_co_u32_e64 v90, s[30:31], 0, v90, s[26:27]
	v_cmp_gt_u32_e64 s[24:25], v62, v74
	v_addc_co_u32_e64 v90, s[30:31], 0, v90, s[20:21]
	v_cmp_gt_u32_e64 s[26:27], v63, v74
	v_addc_co_u32_e64 v90, s[30:31], 0, v90, s[22:23]
	s_waitcnt lgkmcnt(0)
	v_cmp_gt_u32_e64 s[20:21], v96, v74
	v_addc_co_u32_e64 v90, s[30:31], 0, v90, s[24:25]
	v_cmp_gt_u32_e64 s[22:23], v97, v74
	v_addc_co_u32_e64 v90, s[30:31], 0, v90, s[26:27]
	v_addc_co_u32_e64 v90, s[30:31], 0, v90, s[20:21]
	s_nop 1
	v_addc_co_u32_e64 v90, s[30:31], 0, v90, s[22:23]
	ds_read_b128 v[96:99], v58 offset:768
	ds_read_b128 v[60:63], v58 offset:784
	s_waitcnt lgkmcnt(1)
	v_cmp_gt_u32_e64 s[20:21], v96, v75
	v_cmp_gt_u32_e64 s[22:23], v97, v75
	v_cmp_gt_u32_e64 s[24:25], v98, v75
	v_addc_co_u32_e64 v91, s[30:31], 0, v91, s[20:21]
	v_cmp_gt_u32_e64 s[26:27], v99, v75
	v_addc_co_u32_e64 v91, s[30:31], 0, v91, s[22:23]
	ds_read_b128 v[96:99], v58 offset:800
	s_waitcnt lgkmcnt(1)
	v_cmp_gt_u32_e64 s[20:21], v60, v75
	v_addc_co_u32_e64 v91, s[30:31], 0, v91, s[24:25]
	v_cmp_gt_u32_e64 s[22:23], v61, v75
	v_addc_co_u32_e64 v91, s[30:31], 0, v91, s[26:27]
	v_cmp_gt_u32_e64 s[24:25], v62, v75
	v_addc_co_u32_e64 v91, s[30:31], 0, v91, s[20:21]
	v_cmp_gt_u32_e64 s[26:27], v63, v75
	v_addc_co_u32_e64 v91, s[30:31], 0, v91, s[22:23]
	ds_read_b128 v[60:63], v58 offset:816
	s_waitcnt lgkmcnt(1)
	v_cmp_gt_u32_e64 s[20:21], v96, v75
	v_addc_co_u32_e64 v91, s[30:31], 0, v91, s[24:25]
	v_cmp_gt_u32_e64 s[22:23], v97, v75
	v_addc_co_u32_e64 v91, s[30:31], 0, v91, s[26:27]
	v_cmp_gt_u32_e64 s[24:25], v98, v75
	v_addc_co_u32_e64 v91, s[30:31], 0, v91, s[20:21]
	v_cmp_gt_u32_e64 s[26:27], v99, v75
	v_addc_co_u32_e64 v91, s[30:31], 0, v91, s[22:23]
	ds_read_b128 v[96:99], v58 offset:832
	s_waitcnt lgkmcnt(1)
	v_cmp_gt_u32_e64 s[20:21], v60, v75
	v_addc_co_u32_e64 v91, s[30:31], 0, v91, s[24:25]
	v_cmp_gt_u32_e64 s[22:23], v61, v75
	v_addc_co_u32_e64 v91, s[30:31], 0, v91, s[26:27]
	v_cmp_gt_u32_e64 s[24:25], v62, v75
	v_addc_co_u32_e64 v91, s[30:31], 0, v91, s[20:21]
	v_cmp_gt_u32_e64 s[26:27], v63, v75
	v_addc_co_u32_e64 v91, s[30:31], 0, v91, s[22:23]
	ds_read_b128 v[60:63], v58 offset:848
	s_waitcnt lgkmcnt(1)
	v_cmp_gt_u32_e64 s[20:21], v96, v75
	v_addc_co_u32_e64 v91, s[30:31], 0, v91, s[24:25]
	v_cmp_gt_u32_e64 s[22:23], v97, v75
	v_addc_co_u32_e64 v91, s[30:31], 0, v91, s[26:27]
	v_cmp_gt_u32_e64 s[24:25], v98, v75
	v_addc_co_u32_e64 v91, s[30:31], 0, v91, s[20:21]
	v_cmp_gt_u32_e64 s[26:27], v99, v75
	v_addc_co_u32_e64 v91, s[30:31], 0, v91, s[22:23]
	ds_read_b128 v[96:99], v58 offset:864
	s_waitcnt lgkmcnt(1)
	v_cmp_gt_u32_e64 s[20:21], v60, v75
	v_addc_co_u32_e64 v91, s[30:31], 0, v91, s[24:25]
	v_cmp_gt_u32_e64 s[22:23], v61, v75
	v_addc_co_u32_e64 v91, s[30:31], 0, v91, s[26:27]
	v_cmp_gt_u32_e64 s[24:25], v62, v75
	v_addc_co_u32_e64 v91, s[30:31], 0, v91, s[20:21]
	v_cmp_gt_u32_e64 s[26:27], v63, v75
	v_addc_co_u32_e64 v91, s[30:31], 0, v91, s[22:23]
	ds_read_b128 v[60:63], v58 offset:880
	s_waitcnt lgkmcnt(1)
	v_cmp_gt_u32_e64 s[20:21], v96, v75
	v_addc_co_u32_e64 v91, s[30:31], 0, v91, s[24:25]
	v_cmp_gt_u32_e64 s[22:23], v97, v75
	v_addc_co_u32_e64 v91, s[30:31], 0, v91, s[26:27]
	v_cmp_gt_u32_e64 s[24:25], v98, v75
	v_addc_co_u32_e64 v91, s[30:31], 0, v91, s[20:21]
	v_cmp_gt_u32_e64 s[26:27], v99, v75
	v_addc_co_u32_e64 v91, s[30:31], 0, v91, s[22:23]
	ds_read_b128 v[96:99], v58 offset:896
	s_waitcnt lgkmcnt(1)
	v_cmp_gt_u32_e64 s[20:21], v60, v75
	v_addc_co_u32_e64 v91, s[30:31], 0, v91, s[24:25]
	v_cmp_gt_u32_e64 s[22:23], v61, v75
	v_addc_co_u32_e64 v91, s[30:31], 0, v91, s[26:27]
	v_cmp_gt_u32_e64 s[24:25], v62, v75
	v_addc_co_u32_e64 v91, s[30:31], 0, v91, s[20:21]
	v_cmp_gt_u32_e64 s[26:27], v63, v75
	v_addc_co_u32_e64 v91, s[30:31], 0, v91, s[22:23]
	ds_read_b128 v[60:63], v58 offset:912
	s_waitcnt lgkmcnt(1)
	v_cmp_gt_u32_e64 s[20:21], v96, v75
	v_addc_co_u32_e64 v91, s[30:31], 0, v91, s[24:25]
	v_cmp_gt_u32_e64 s[22:23], v97, v75
	v_addc_co_u32_e64 v91, s[30:31], 0, v91, s[26:27]
	v_cmp_gt_u32_e64 s[24:25], v98, v75
	v_addc_co_u32_e64 v91, s[30:31], 0, v91, s[20:21]
	v_cmp_gt_u32_e64 s[26:27], v99, v75
	v_addc_co_u32_e64 v91, s[30:31], 0, v91, s[22:23]
	ds_read_b128 v[96:99], v58 offset:928
	s_waitcnt lgkmcnt(1)
	v_cmp_gt_u32_e64 s[20:21], v60, v75
	v_addc_co_u32_e64 v91, s[30:31], 0, v91, s[24:25]
	v_cmp_gt_u32_e64 s[22:23], v61, v75
	v_addc_co_u32_e64 v91, s[30:31], 0, v91, s[26:27]
	v_cmp_gt_u32_e64 s[24:25], v62, v75
	v_addc_co_u32_e64 v91, s[30:31], 0, v91, s[20:21]
	v_cmp_gt_u32_e64 s[26:27], v63, v75
	v_addc_co_u32_e64 v91, s[30:31], 0, v91, s[22:23]
	ds_read_b128 v[60:63], v58 offset:944
	s_waitcnt lgkmcnt(1)
	v_cmp_gt_u32_e64 s[20:21], v96, v75
	v_addc_co_u32_e64 v91, s[30:31], 0, v91, s[24:25]
	v_cmp_gt_u32_e64 s[22:23], v97, v75
	v_addc_co_u32_e64 v91, s[30:31], 0, v91, s[26:27]
	v_cmp_gt_u32_e64 s[24:25], v98, v75
	v_addc_co_u32_e64 v91, s[30:31], 0, v91, s[20:21]
	v_cmp_gt_u32_e64 s[26:27], v99, v75
	v_addc_co_u32_e64 v91, s[30:31], 0, v91, s[22:23]
	ds_read_b128 v[96:99], v58 offset:960
	s_waitcnt lgkmcnt(1)
	v_cmp_gt_u32_e64 s[20:21], v60, v75
	v_addc_co_u32_e64 v91, s[30:31], 0, v91, s[24:25]
	v_cmp_gt_u32_e64 s[22:23], v61, v75
	v_addc_co_u32_e64 v91, s[30:31], 0, v91, s[26:27]
	v_cmp_gt_u32_e64 s[24:25], v62, v75
	v_addc_co_u32_e64 v91, s[30:31], 0, v91, s[20:21]
	v_cmp_gt_u32_e64 s[26:27], v63, v75
	v_addc_co_u32_e64 v91, s[30:31], 0, v91, s[22:23]
	s_waitcnt lgkmcnt(0)
	v_cmp_gt_u32_e64 s[20:21], v96, v75
	v_addc_co_u32_e64 v91, s[30:31], 0, v91, s[24:25]
	v_cmp_gt_u32_e64 s[22:23], v97, v75
	v_addc_co_u32_e64 v91, s[30:31], 0, v91, s[26:27]
	v_addc_co_u32_e64 v91, s[30:31], 0, v91, s[20:21]
	s_nop 1
	v_addc_co_u32_e64 v91, s[30:31], 0, v91, s[22:23]
	ds_read_b128 v[96:99], v58 offset:1024
	ds_read_b128 v[60:63], v58 offset:1040
	s_waitcnt lgkmcnt(1)
	v_cmp_gt_u32_e64 s[20:21], v96, v76
	v_cmp_gt_u32_e64 s[22:23], v97, v76
	v_cmp_gt_u32_e64 s[24:25], v98, v76
	v_addc_co_u32_e64 v92, s[30:31], 0, v92, s[20:21]
	v_cmp_gt_u32_e64 s[26:27], v99, v76
	v_addc_co_u32_e64 v92, s[30:31], 0, v92, s[22:23]
	ds_read_b128 v[96:99], v58 offset:1056
	s_waitcnt lgkmcnt(1)
	v_cmp_gt_u32_e64 s[20:21], v60, v76
	v_addc_co_u32_e64 v92, s[30:31], 0, v92, s[24:25]
	v_cmp_gt_u32_e64 s[22:23], v61, v76
	v_addc_co_u32_e64 v92, s[30:31], 0, v92, s[26:27]
	v_cmp_gt_u32_e64 s[24:25], v62, v76
	v_addc_co_u32_e64 v92, s[30:31], 0, v92, s[20:21]
	v_cmp_gt_u32_e64 s[26:27], v63, v76
	v_addc_co_u32_e64 v92, s[30:31], 0, v92, s[22:23]
	ds_read_b128 v[60:63], v58 offset:1072
	s_waitcnt lgkmcnt(1)
	v_cmp_gt_u32_e64 s[20:21], v96, v76
	v_addc_co_u32_e64 v92, s[30:31], 0, v92, s[24:25]
	v_cmp_gt_u32_e64 s[22:23], v97, v76
	v_addc_co_u32_e64 v92, s[30:31], 0, v92, s[26:27]
	v_cmp_gt_u32_e64 s[24:25], v98, v76
	v_addc_co_u32_e64 v92, s[30:31], 0, v92, s[20:21]
	v_cmp_gt_u32_e64 s[26:27], v99, v76
	v_addc_co_u32_e64 v92, s[30:31], 0, v92, s[22:23]
	ds_read_b128 v[96:99], v58 offset:1088
	s_waitcnt lgkmcnt(1)
	v_cmp_gt_u32_e64 s[20:21], v60, v76
	v_addc_co_u32_e64 v92, s[30:31], 0, v92, s[24:25]
	v_cmp_gt_u32_e64 s[22:23], v61, v76
	v_addc_co_u32_e64 v92, s[30:31], 0, v92, s[26:27]
	v_cmp_gt_u32_e64 s[24:25], v62, v76
	v_addc_co_u32_e64 v92, s[30:31], 0, v92, s[20:21]
	v_cmp_gt_u32_e64 s[26:27], v63, v76
	v_addc_co_u32_e64 v92, s[30:31], 0, v92, s[22:23]
	ds_read_b128 v[60:63], v58 offset:1104
	s_waitcnt lgkmcnt(1)
	v_cmp_gt_u32_e64 s[20:21], v96, v76
	v_addc_co_u32_e64 v92, s[30:31], 0, v92, s[24:25]
	v_cmp_gt_u32_e64 s[22:23], v97, v76
	v_addc_co_u32_e64 v92, s[30:31], 0, v92, s[26:27]
	v_cmp_gt_u32_e64 s[24:25], v98, v76
	v_addc_co_u32_e64 v92, s[30:31], 0, v92, s[20:21]
	v_cmp_gt_u32_e64 s[26:27], v99, v76
	v_addc_co_u32_e64 v92, s[30:31], 0, v92, s[22:23]
	ds_read_b128 v[96:99], v58 offset:1120
	s_waitcnt lgkmcnt(1)
	v_cmp_gt_u32_e64 s[20:21], v60, v76
	v_addc_co_u32_e64 v92, s[30:31], 0, v92, s[24:25]
	v_cmp_gt_u32_e64 s[22:23], v61, v76
	v_addc_co_u32_e64 v92, s[30:31], 0, v92, s[26:27]
	v_cmp_gt_u32_e64 s[24:25], v62, v76
	v_addc_co_u32_e64 v92, s[30:31], 0, v92, s[20:21]
	v_cmp_gt_u32_e64 s[26:27], v63, v76
	v_addc_co_u32_e64 v92, s[30:31], 0, v92, s[22:23]
	ds_read_b128 v[60:63], v58 offset:1136
	s_waitcnt lgkmcnt(1)
	v_cmp_gt_u32_e64 s[20:21], v96, v76
	v_addc_co_u32_e64 v92, s[30:31], 0, v92, s[24:25]
	v_cmp_gt_u32_e64 s[22:23], v97, v76
	v_addc_co_u32_e64 v92, s[30:31], 0, v92, s[26:27]
	v_cmp_gt_u32_e64 s[24:25], v98, v76
	v_addc_co_u32_e64 v92, s[30:31], 0, v92, s[20:21]
	v_cmp_gt_u32_e64 s[26:27], v99, v76
	v_addc_co_u32_e64 v92, s[30:31], 0, v92, s[22:23]
	ds_read_b128 v[96:99], v58 offset:1152
	s_waitcnt lgkmcnt(1)
	v_cmp_gt_u32_e64 s[20:21], v60, v76
	v_addc_co_u32_e64 v92, s[30:31], 0, v92, s[24:25]
	v_cmp_gt_u32_e64 s[22:23], v61, v76
	v_addc_co_u32_e64 v92, s[30:31], 0, v92, s[26:27]
	v_cmp_gt_u32_e64 s[24:25], v62, v76
	v_addc_co_u32_e64 v92, s[30:31], 0, v92, s[20:21]
	v_cmp_gt_u32_e64 s[26:27], v63, v76
	v_addc_co_u32_e64 v92, s[30:31], 0, v92, s[22:23]
	ds_read_b128 v[60:63], v58 offset:1168
	s_waitcnt lgkmcnt(1)
	v_cmp_gt_u32_e64 s[20:21], v96, v76
	v_addc_co_u32_e64 v92, s[30:31], 0, v92, s[24:25]
	v_cmp_gt_u32_e64 s[22:23], v97, v76
	v_addc_co_u32_e64 v92, s[30:31], 0, v92, s[26:27]
	v_cmp_gt_u32_e64 s[24:25], v98, v76
	v_addc_co_u32_e64 v92, s[30:31], 0, v92, s[20:21]
	v_cmp_gt_u32_e64 s[26:27], v99, v76
	v_addc_co_u32_e64 v92, s[30:31], 0, v92, s[22:23]
	ds_read_b128 v[96:99], v58 offset:1184
	s_waitcnt lgkmcnt(1)
	v_cmp_gt_u32_e64 s[20:21], v60, v76
	v_addc_co_u32_e64 v92, s[30:31], 0, v92, s[24:25]
	v_cmp_gt_u32_e64 s[22:23], v61, v76
	v_addc_co_u32_e64 v92, s[30:31], 0, v92, s[26:27]
	v_cmp_gt_u32_e64 s[24:25], v62, v76
	v_addc_co_u32_e64 v92, s[30:31], 0, v92, s[20:21]
	v_cmp_gt_u32_e64 s[26:27], v63, v76
	v_addc_co_u32_e64 v92, s[30:31], 0, v92, s[22:23]
	ds_read_b128 v[60:63], v58 offset:1200
	s_waitcnt lgkmcnt(1)
	v_cmp_gt_u32_e64 s[20:21], v96, v76
	v_addc_co_u32_e64 v92, s[30:31], 0, v92, s[24:25]
	v_cmp_gt_u32_e64 s[22:23], v97, v76
	v_addc_co_u32_e64 v92, s[30:31], 0, v92, s[26:27]
	v_cmp_gt_u32_e64 s[24:25], v98, v76
	v_addc_co_u32_e64 v92, s[30:31], 0, v92, s[20:21]
	v_cmp_gt_u32_e64 s[26:27], v99, v76
	v_addc_co_u32_e64 v92, s[30:31], 0, v92, s[22:23]
	ds_read_b128 v[96:99], v58 offset:1216
	s_waitcnt lgkmcnt(1)
	v_cmp_gt_u32_e64 s[20:21], v60, v76
	v_addc_co_u32_e64 v92, s[30:31], 0, v92, s[24:25]
	v_cmp_gt_u32_e64 s[22:23], v61, v76
	v_addc_co_u32_e64 v92, s[30:31], 0, v92, s[26:27]
	v_cmp_gt_u32_e64 s[24:25], v62, v76
	v_addc_co_u32_e64 v92, s[30:31], 0, v92, s[20:21]
	v_cmp_gt_u32_e64 s[26:27], v63, v76
	v_addc_co_u32_e64 v92, s[30:31], 0, v92, s[22:23]
	s_waitcnt lgkmcnt(0)
	v_cmp_gt_u32_e64 s[20:21], v96, v76
	v_addc_co_u32_e64 v92, s[30:31], 0, v92, s[24:25]
	v_cmp_gt_u32_e64 s[22:23], v97, v76
	v_addc_co_u32_e64 v92, s[30:31], 0, v92, s[26:27]
	v_addc_co_u32_e64 v92, s[30:31], 0, v92, s[20:21]
	s_nop 1
	v_addc_co_u32_e64 v92, s[30:31], 0, v92, s[22:23]
	ds_read_b128 v[96:99], v58 offset:1280
	ds_read_b128 v[60:63], v58 offset:1296
	s_waitcnt lgkmcnt(1)
	v_cmp_gt_u32_e64 s[20:21], v96, v77
	v_cmp_gt_u32_e64 s[22:23], v97, v77
	v_cmp_gt_u32_e64 s[24:25], v98, v77
	v_addc_co_u32_e64 v93, s[30:31], 0, v93, s[20:21]
	v_cmp_gt_u32_e64 s[26:27], v99, v77
	v_addc_co_u32_e64 v93, s[30:31], 0, v93, s[22:23]
	ds_read_b128 v[96:99], v58 offset:1312
	s_waitcnt lgkmcnt(1)
	v_cmp_gt_u32_e64 s[20:21], v60, v77
	v_addc_co_u32_e64 v93, s[30:31], 0, v93, s[24:25]
	v_cmp_gt_u32_e64 s[22:23], v61, v77
	v_addc_co_u32_e64 v93, s[30:31], 0, v93, s[26:27]
	v_cmp_gt_u32_e64 s[24:25], v62, v77
	v_addc_co_u32_e64 v93, s[30:31], 0, v93, s[20:21]
	v_cmp_gt_u32_e64 s[26:27], v63, v77
	v_addc_co_u32_e64 v93, s[30:31], 0, v93, s[22:23]
	ds_read_b128 v[60:63], v58 offset:1328
	s_waitcnt lgkmcnt(1)
	v_cmp_gt_u32_e64 s[20:21], v96, v77
	v_addc_co_u32_e64 v93, s[30:31], 0, v93, s[24:25]
	v_cmp_gt_u32_e64 s[22:23], v97, v77
	v_addc_co_u32_e64 v93, s[30:31], 0, v93, s[26:27]
	v_cmp_gt_u32_e64 s[24:25], v98, v77
	v_addc_co_u32_e64 v93, s[30:31], 0, v93, s[20:21]
	v_cmp_gt_u32_e64 s[26:27], v99, v77
	v_addc_co_u32_e64 v93, s[30:31], 0, v93, s[22:23]
	ds_read_b128 v[96:99], v58 offset:1344
	s_waitcnt lgkmcnt(1)
	v_cmp_gt_u32_e64 s[20:21], v60, v77
	v_addc_co_u32_e64 v93, s[30:31], 0, v93, s[24:25]
	v_cmp_gt_u32_e64 s[22:23], v61, v77
	v_addc_co_u32_e64 v93, s[30:31], 0, v93, s[26:27]
	v_cmp_gt_u32_e64 s[24:25], v62, v77
	v_addc_co_u32_e64 v93, s[30:31], 0, v93, s[20:21]
	v_cmp_gt_u32_e64 s[26:27], v63, v77
	v_addc_co_u32_e64 v93, s[30:31], 0, v93, s[22:23]
	ds_read_b128 v[60:63], v58 offset:1360
	s_waitcnt lgkmcnt(1)
	v_cmp_gt_u32_e64 s[20:21], v96, v77
	v_addc_co_u32_e64 v93, s[30:31], 0, v93, s[24:25]
	v_cmp_gt_u32_e64 s[22:23], v97, v77
	v_addc_co_u32_e64 v93, s[30:31], 0, v93, s[26:27]
	v_cmp_gt_u32_e64 s[24:25], v98, v77
	v_addc_co_u32_e64 v93, s[30:31], 0, v93, s[20:21]
	v_cmp_gt_u32_e64 s[26:27], v99, v77
	v_addc_co_u32_e64 v93, s[30:31], 0, v93, s[22:23]
	ds_read_b128 v[96:99], v58 offset:1376
	s_waitcnt lgkmcnt(1)
	v_cmp_gt_u32_e64 s[20:21], v60, v77
	v_addc_co_u32_e64 v93, s[30:31], 0, v93, s[24:25]
	v_cmp_gt_u32_e64 s[22:23], v61, v77
	v_addc_co_u32_e64 v93, s[30:31], 0, v93, s[26:27]
	v_cmp_gt_u32_e64 s[24:25], v62, v77
	v_addc_co_u32_e64 v93, s[30:31], 0, v93, s[20:21]
	v_cmp_gt_u32_e64 s[26:27], v63, v77
	v_addc_co_u32_e64 v93, s[30:31], 0, v93, s[22:23]
	ds_read_b128 v[60:63], v58 offset:1392
	s_waitcnt lgkmcnt(1)
	v_cmp_gt_u32_e64 s[20:21], v96, v77
	v_addc_co_u32_e64 v93, s[30:31], 0, v93, s[24:25]
	v_cmp_gt_u32_e64 s[22:23], v97, v77
	v_addc_co_u32_e64 v93, s[30:31], 0, v93, s[26:27]
	v_cmp_gt_u32_e64 s[24:25], v98, v77
	v_addc_co_u32_e64 v93, s[30:31], 0, v93, s[20:21]
	v_cmp_gt_u32_e64 s[26:27], v99, v77
	v_addc_co_u32_e64 v93, s[30:31], 0, v93, s[22:23]
	ds_read_b128 v[96:99], v58 offset:1408
	s_waitcnt lgkmcnt(1)
	v_cmp_gt_u32_e64 s[20:21], v60, v77
	v_addc_co_u32_e64 v93, s[30:31], 0, v93, s[24:25]
	v_cmp_gt_u32_e64 s[22:23], v61, v77
	v_addc_co_u32_e64 v93, s[30:31], 0, v93, s[26:27]
	v_cmp_gt_u32_e64 s[24:25], v62, v77
	v_addc_co_u32_e64 v93, s[30:31], 0, v93, s[20:21]
	v_cmp_gt_u32_e64 s[26:27], v63, v77
	v_addc_co_u32_e64 v93, s[30:31], 0, v93, s[22:23]
	ds_read_b128 v[60:63], v58 offset:1424
	s_waitcnt lgkmcnt(1)
	v_cmp_gt_u32_e64 s[20:21], v96, v77
	v_addc_co_u32_e64 v93, s[30:31], 0, v93, s[24:25]
	v_cmp_gt_u32_e64 s[22:23], v97, v77
	v_addc_co_u32_e64 v93, s[30:31], 0, v93, s[26:27]
	v_cmp_gt_u32_e64 s[24:25], v98, v77
	v_addc_co_u32_e64 v93, s[30:31], 0, v93, s[20:21]
	v_cmp_gt_u32_e64 s[26:27], v99, v77
	v_addc_co_u32_e64 v93, s[30:31], 0, v93, s[22:23]
	ds_read_b128 v[96:99], v58 offset:1440
	s_waitcnt lgkmcnt(1)
	v_cmp_gt_u32_e64 s[20:21], v60, v77
	v_addc_co_u32_e64 v93, s[30:31], 0, v93, s[24:25]
	v_cmp_gt_u32_e64 s[22:23], v61, v77
	v_addc_co_u32_e64 v93, s[30:31], 0, v93, s[26:27]
	v_cmp_gt_u32_e64 s[24:25], v62, v77
	v_addc_co_u32_e64 v93, s[30:31], 0, v93, s[20:21]
	v_cmp_gt_u32_e64 s[26:27], v63, v77
	v_addc_co_u32_e64 v93, s[30:31], 0, v93, s[22:23]
	ds_read_b128 v[60:63], v58 offset:1456
	s_waitcnt lgkmcnt(1)
	v_cmp_gt_u32_e64 s[20:21], v96, v77
	v_addc_co_u32_e64 v93, s[30:31], 0, v93, s[24:25]
	v_cmp_gt_u32_e64 s[22:23], v97, v77
	v_addc_co_u32_e64 v93, s[30:31], 0, v93, s[26:27]
	v_cmp_gt_u32_e64 s[24:25], v98, v77
	v_addc_co_u32_e64 v93, s[30:31], 0, v93, s[20:21]
	v_cmp_gt_u32_e64 s[26:27], v99, v77
	v_addc_co_u32_e64 v93, s[30:31], 0, v93, s[22:23]
	ds_read_b128 v[96:99], v58 offset:1472
	s_waitcnt lgkmcnt(1)
	v_cmp_gt_u32_e64 s[20:21], v60, v77
	v_addc_co_u32_e64 v93, s[30:31], 0, v93, s[24:25]
	v_cmp_gt_u32_e64 s[22:23], v61, v77
	v_addc_co_u32_e64 v93, s[30:31], 0, v93, s[26:27]
	v_cmp_gt_u32_e64 s[24:25], v62, v77
	v_addc_co_u32_e64 v93, s[30:31], 0, v93, s[20:21]
	v_cmp_gt_u32_e64 s[26:27], v63, v77
	v_addc_co_u32_e64 v93, s[30:31], 0, v93, s[22:23]
	s_waitcnt lgkmcnt(0)
	v_cmp_gt_u32_e64 s[20:21], v96, v77
	v_addc_co_u32_e64 v93, s[30:31], 0, v93, s[24:25]
	v_cmp_gt_u32_e64 s[22:23], v97, v77
	v_addc_co_u32_e64 v93, s[30:31], 0, v93, s[26:27]
	v_addc_co_u32_e64 v93, s[30:31], 0, v93, s[20:21]
	s_nop 1
	v_addc_co_u32_e64 v93, s[30:31], 0, v93, s[22:23]
	ds_read_b128 v[96:99], v58 offset:1536
	ds_read_b128 v[60:63], v58 offset:1552
	s_waitcnt lgkmcnt(1)
	v_cmp_gt_u32_e64 s[20:21], v96, v78
	v_cmp_gt_u32_e64 s[22:23], v97, v78
	v_cmp_gt_u32_e64 s[24:25], v98, v78
	v_addc_co_u32_e64 v94, s[30:31], 0, v94, s[20:21]
	v_cmp_gt_u32_e64 s[26:27], v99, v78
	v_addc_co_u32_e64 v94, s[30:31], 0, v94, s[22:23]
	ds_read_b128 v[96:99], v58 offset:1568
	s_waitcnt lgkmcnt(1)
	v_cmp_gt_u32_e64 s[20:21], v60, v78
	v_addc_co_u32_e64 v94, s[30:31], 0, v94, s[24:25]
	v_cmp_gt_u32_e64 s[22:23], v61, v78
	v_addc_co_u32_e64 v94, s[30:31], 0, v94, s[26:27]
	v_cmp_gt_u32_e64 s[24:25], v62, v78
	v_addc_co_u32_e64 v94, s[30:31], 0, v94, s[20:21]
	v_cmp_gt_u32_e64 s[26:27], v63, v78
	v_addc_co_u32_e64 v94, s[30:31], 0, v94, s[22:23]
	ds_read_b128 v[60:63], v58 offset:1584
	s_waitcnt lgkmcnt(1)
	v_cmp_gt_u32_e64 s[20:21], v96, v78
	v_addc_co_u32_e64 v94, s[30:31], 0, v94, s[24:25]
	v_cmp_gt_u32_e64 s[22:23], v97, v78
	v_addc_co_u32_e64 v94, s[30:31], 0, v94, s[26:27]
	v_cmp_gt_u32_e64 s[24:25], v98, v78
	v_addc_co_u32_e64 v94, s[30:31], 0, v94, s[20:21]
	v_cmp_gt_u32_e64 s[26:27], v99, v78
	v_addc_co_u32_e64 v94, s[30:31], 0, v94, s[22:23]
	ds_read_b128 v[96:99], v58 offset:1600
	s_waitcnt lgkmcnt(1)
	v_cmp_gt_u32_e64 s[20:21], v60, v78
	v_addc_co_u32_e64 v94, s[30:31], 0, v94, s[24:25]
	v_cmp_gt_u32_e64 s[22:23], v61, v78
	v_addc_co_u32_e64 v94, s[30:31], 0, v94, s[26:27]
	v_cmp_gt_u32_e64 s[24:25], v62, v78
	v_addc_co_u32_e64 v94, s[30:31], 0, v94, s[20:21]
	v_cmp_gt_u32_e64 s[26:27], v63, v78
	v_addc_co_u32_e64 v94, s[30:31], 0, v94, s[22:23]
	ds_read_b128 v[60:63], v58 offset:1616
	s_waitcnt lgkmcnt(1)
	v_cmp_gt_u32_e64 s[20:21], v96, v78
	v_addc_co_u32_e64 v94, s[30:31], 0, v94, s[24:25]
	v_cmp_gt_u32_e64 s[22:23], v97, v78
	v_addc_co_u32_e64 v94, s[30:31], 0, v94, s[26:27]
	v_cmp_gt_u32_e64 s[24:25], v98, v78
	v_addc_co_u32_e64 v94, s[30:31], 0, v94, s[20:21]
	v_cmp_gt_u32_e64 s[26:27], v99, v78
	v_addc_co_u32_e64 v94, s[30:31], 0, v94, s[22:23]
	ds_read_b128 v[96:99], v58 offset:1632
	s_waitcnt lgkmcnt(1)
	v_cmp_gt_u32_e64 s[20:21], v60, v78
	v_addc_co_u32_e64 v94, s[30:31], 0, v94, s[24:25]
	v_cmp_gt_u32_e64 s[22:23], v61, v78
	v_addc_co_u32_e64 v94, s[30:31], 0, v94, s[26:27]
	v_cmp_gt_u32_e64 s[24:25], v62, v78
	v_addc_co_u32_e64 v94, s[30:31], 0, v94, s[20:21]
	v_cmp_gt_u32_e64 s[26:27], v63, v78
	v_addc_co_u32_e64 v94, s[30:31], 0, v94, s[22:23]
	ds_read_b128 v[60:63], v58 offset:1648
	s_waitcnt lgkmcnt(1)
	v_cmp_gt_u32_e64 s[20:21], v96, v78
	v_addc_co_u32_e64 v94, s[30:31], 0, v94, s[24:25]
	v_cmp_gt_u32_e64 s[22:23], v97, v78
	v_addc_co_u32_e64 v94, s[30:31], 0, v94, s[26:27]
	v_cmp_gt_u32_e64 s[24:25], v98, v78
	v_addc_co_u32_e64 v94, s[30:31], 0, v94, s[20:21]
	v_cmp_gt_u32_e64 s[26:27], v99, v78
	v_addc_co_u32_e64 v94, s[30:31], 0, v94, s[22:23]
	ds_read_b128 v[96:99], v58 offset:1664
	s_waitcnt lgkmcnt(1)
	v_cmp_gt_u32_e64 s[20:21], v60, v78
	v_addc_co_u32_e64 v94, s[30:31], 0, v94, s[24:25]
	v_cmp_gt_u32_e64 s[22:23], v61, v78
	v_addc_co_u32_e64 v94, s[30:31], 0, v94, s[26:27]
	v_cmp_gt_u32_e64 s[24:25], v62, v78
	v_addc_co_u32_e64 v94, s[30:31], 0, v94, s[20:21]
	v_cmp_gt_u32_e64 s[26:27], v63, v78
	v_addc_co_u32_e64 v94, s[30:31], 0, v94, s[22:23]
	ds_read_b128 v[60:63], v58 offset:1680
	s_waitcnt lgkmcnt(1)
	v_cmp_gt_u32_e64 s[20:21], v96, v78
	v_addc_co_u32_e64 v94, s[30:31], 0, v94, s[24:25]
	v_cmp_gt_u32_e64 s[22:23], v97, v78
	v_addc_co_u32_e64 v94, s[30:31], 0, v94, s[26:27]
	v_cmp_gt_u32_e64 s[24:25], v98, v78
	v_addc_co_u32_e64 v94, s[30:31], 0, v94, s[20:21]
	v_cmp_gt_u32_e64 s[26:27], v99, v78
	v_addc_co_u32_e64 v94, s[30:31], 0, v94, s[22:23]
	ds_read_b128 v[96:99], v58 offset:1696
	s_waitcnt lgkmcnt(1)
	v_cmp_gt_u32_e64 s[20:21], v60, v78
	v_addc_co_u32_e64 v94, s[30:31], 0, v94, s[24:25]
	v_cmp_gt_u32_e64 s[22:23], v61, v78
	v_addc_co_u32_e64 v94, s[30:31], 0, v94, s[26:27]
	v_cmp_gt_u32_e64 s[24:25], v62, v78
	v_addc_co_u32_e64 v94, s[30:31], 0, v94, s[20:21]
	v_cmp_gt_u32_e64 s[26:27], v63, v78
	v_addc_co_u32_e64 v94, s[30:31], 0, v94, s[22:23]
	ds_read_b128 v[60:63], v58 offset:1712
	s_waitcnt lgkmcnt(1)
	v_cmp_gt_u32_e64 s[20:21], v96, v78
	v_addc_co_u32_e64 v94, s[30:31], 0, v94, s[24:25]
	v_cmp_gt_u32_e64 s[22:23], v97, v78
	v_addc_co_u32_e64 v94, s[30:31], 0, v94, s[26:27]
	v_cmp_gt_u32_e64 s[24:25], v98, v78
	v_addc_co_u32_e64 v94, s[30:31], 0, v94, s[20:21]
	v_cmp_gt_u32_e64 s[26:27], v99, v78
	v_addc_co_u32_e64 v94, s[30:31], 0, v94, s[22:23]
	ds_read_b128 v[96:99], v58 offset:1728
	s_waitcnt lgkmcnt(1)
	v_cmp_gt_u32_e64 s[20:21], v60, v78
	v_addc_co_u32_e64 v94, s[30:31], 0, v94, s[24:25]
	v_cmp_gt_u32_e64 s[22:23], v61, v78
	v_addc_co_u32_e64 v94, s[30:31], 0, v94, s[26:27]
	v_cmp_gt_u32_e64 s[24:25], v62, v78
	v_addc_co_u32_e64 v94, s[30:31], 0, v94, s[20:21]
	v_cmp_gt_u32_e64 s[26:27], v63, v78
	v_addc_co_u32_e64 v94, s[30:31], 0, v94, s[22:23]
	s_waitcnt lgkmcnt(0)
	v_cmp_gt_u32_e64 s[20:21], v96, v78
	v_addc_co_u32_e64 v94, s[30:31], 0, v94, s[24:25]
	v_cmp_gt_u32_e64 s[22:23], v97, v78
	v_addc_co_u32_e64 v94, s[30:31], 0, v94, s[26:27]
	v_addc_co_u32_e64 v94, s[30:31], 0, v94, s[20:21]
	s_nop 1
	v_addc_co_u32_e64 v94, s[30:31], 0, v94, s[22:23]
	ds_read_b128 v[96:99], v58 offset:1792
	ds_read_b128 v[60:63], v58 offset:1808
	s_waitcnt lgkmcnt(1)
	v_cmp_gt_u32_e64 s[20:21], v96, v79
	v_cmp_gt_u32_e64 s[22:23], v97, v79
	v_cmp_gt_u32_e64 s[24:25], v98, v79
	v_addc_co_u32_e64 v95, s[30:31], 0, v95, s[20:21]
	v_cmp_gt_u32_e64 s[26:27], v99, v79
	v_addc_co_u32_e64 v95, s[30:31], 0, v95, s[22:23]
	ds_read_b128 v[96:99], v58 offset:1824
	s_waitcnt lgkmcnt(1)
	v_cmp_gt_u32_e64 s[20:21], v60, v79
	v_addc_co_u32_e64 v95, s[30:31], 0, v95, s[24:25]
	v_cmp_gt_u32_e64 s[22:23], v61, v79
	v_addc_co_u32_e64 v95, s[30:31], 0, v95, s[26:27]
	v_cmp_gt_u32_e64 s[24:25], v62, v79
	v_addc_co_u32_e64 v95, s[30:31], 0, v95, s[20:21]
	v_cmp_gt_u32_e64 s[26:27], v63, v79
	v_addc_co_u32_e64 v95, s[30:31], 0, v95, s[22:23]
	ds_read_b128 v[60:63], v58 offset:1840
	s_waitcnt lgkmcnt(1)
	v_cmp_gt_u32_e64 s[20:21], v96, v79
	v_addc_co_u32_e64 v95, s[30:31], 0, v95, s[24:25]
	v_cmp_gt_u32_e64 s[22:23], v97, v79
	v_addc_co_u32_e64 v95, s[30:31], 0, v95, s[26:27]
	v_cmp_gt_u32_e64 s[24:25], v98, v79
	v_addc_co_u32_e64 v95, s[30:31], 0, v95, s[20:21]
	v_cmp_gt_u32_e64 s[26:27], v99, v79
	v_addc_co_u32_e64 v95, s[30:31], 0, v95, s[22:23]
	ds_read_b128 v[96:99], v58 offset:1856
	s_waitcnt lgkmcnt(1)
	v_cmp_gt_u32_e64 s[20:21], v60, v79
	v_addc_co_u32_e64 v95, s[30:31], 0, v95, s[24:25]
	v_cmp_gt_u32_e64 s[22:23], v61, v79
	v_addc_co_u32_e64 v95, s[30:31], 0, v95, s[26:27]
	v_cmp_gt_u32_e64 s[24:25], v62, v79
	v_addc_co_u32_e64 v95, s[30:31], 0, v95, s[20:21]
	v_cmp_gt_u32_e64 s[26:27], v63, v79
	v_addc_co_u32_e64 v95, s[30:31], 0, v95, s[22:23]
	ds_read_b128 v[60:63], v58 offset:1872
	s_waitcnt lgkmcnt(1)
	v_cmp_gt_u32_e64 s[20:21], v96, v79
	v_addc_co_u32_e64 v95, s[30:31], 0, v95, s[24:25]
	v_cmp_gt_u32_e64 s[22:23], v97, v79
	v_addc_co_u32_e64 v95, s[30:31], 0, v95, s[26:27]
	v_cmp_gt_u32_e64 s[24:25], v98, v79
	v_addc_co_u32_e64 v95, s[30:31], 0, v95, s[20:21]
	v_cmp_gt_u32_e64 s[26:27], v99, v79
	v_addc_co_u32_e64 v95, s[30:31], 0, v95, s[22:23]
	ds_read_b128 v[96:99], v58 offset:1888
	s_waitcnt lgkmcnt(1)
	v_cmp_gt_u32_e64 s[20:21], v60, v79
	v_addc_co_u32_e64 v95, s[30:31], 0, v95, s[24:25]
	v_cmp_gt_u32_e64 s[22:23], v61, v79
	v_addc_co_u32_e64 v95, s[30:31], 0, v95, s[26:27]
	v_cmp_gt_u32_e64 s[24:25], v62, v79
	v_addc_co_u32_e64 v95, s[30:31], 0, v95, s[20:21]
	v_cmp_gt_u32_e64 s[26:27], v63, v79
	v_addc_co_u32_e64 v95, s[30:31], 0, v95, s[22:23]
	ds_read_b128 v[60:63], v58 offset:1904
	s_waitcnt lgkmcnt(1)
	v_cmp_gt_u32_e64 s[20:21], v96, v79
	v_addc_co_u32_e64 v95, s[30:31], 0, v95, s[24:25]
	v_cmp_gt_u32_e64 s[22:23], v97, v79
	v_addc_co_u32_e64 v95, s[30:31], 0, v95, s[26:27]
	v_cmp_gt_u32_e64 s[24:25], v98, v79
	v_addc_co_u32_e64 v95, s[30:31], 0, v95, s[20:21]
	v_cmp_gt_u32_e64 s[26:27], v99, v79
	v_addc_co_u32_e64 v95, s[30:31], 0, v95, s[22:23]
	ds_read_b128 v[96:99], v58 offset:1920
	s_waitcnt lgkmcnt(1)
	v_cmp_gt_u32_e64 s[20:21], v60, v79
	v_addc_co_u32_e64 v95, s[30:31], 0, v95, s[24:25]
	v_cmp_gt_u32_e64 s[22:23], v61, v79
	v_addc_co_u32_e64 v95, s[30:31], 0, v95, s[26:27]
	v_cmp_gt_u32_e64 s[24:25], v62, v79
	v_addc_co_u32_e64 v95, s[30:31], 0, v95, s[20:21]
	v_cmp_gt_u32_e64 s[26:27], v63, v79
	v_addc_co_u32_e64 v95, s[30:31], 0, v95, s[22:23]
	ds_read_b128 v[60:63], v58 offset:1936
	s_waitcnt lgkmcnt(1)
	v_cmp_gt_u32_e64 s[20:21], v96, v79
	v_addc_co_u32_e64 v95, s[30:31], 0, v95, s[24:25]
	v_cmp_gt_u32_e64 s[22:23], v97, v79
	v_addc_co_u32_e64 v95, s[30:31], 0, v95, s[26:27]
	v_cmp_gt_u32_e64 s[24:25], v98, v79
	v_addc_co_u32_e64 v95, s[30:31], 0, v95, s[20:21]
	v_cmp_gt_u32_e64 s[26:27], v99, v79
	v_addc_co_u32_e64 v95, s[30:31], 0, v95, s[22:23]
	ds_read_b128 v[96:99], v58 offset:1952
	s_waitcnt lgkmcnt(1)
	v_cmp_gt_u32_e64 s[20:21], v60, v79
	v_addc_co_u32_e64 v95, s[30:31], 0, v95, s[24:25]
	v_cmp_gt_u32_e64 s[22:23], v61, v79
	v_addc_co_u32_e64 v95, s[30:31], 0, v95, s[26:27]
	v_cmp_gt_u32_e64 s[24:25], v62, v79
	v_addc_co_u32_e64 v95, s[30:31], 0, v95, s[20:21]
	v_cmp_gt_u32_e64 s[26:27], v63, v79
	v_addc_co_u32_e64 v95, s[30:31], 0, v95, s[22:23]
	ds_read_b128 v[60:63], v58 offset:1968
	s_waitcnt lgkmcnt(1)
	v_cmp_gt_u32_e64 s[20:21], v96, v79
	v_addc_co_u32_e64 v95, s[30:31], 0, v95, s[24:25]
	v_cmp_gt_u32_e64 s[22:23], v97, v79
	v_addc_co_u32_e64 v95, s[30:31], 0, v95, s[26:27]
	v_cmp_gt_u32_e64 s[24:25], v98, v79
	v_addc_co_u32_e64 v95, s[30:31], 0, v95, s[20:21]
	v_cmp_gt_u32_e64 s[26:27], v99, v79
	v_addc_co_u32_e64 v95, s[30:31], 0, v95, s[22:23]
	ds_read_b128 v[96:99], v58 offset:1984
	s_waitcnt lgkmcnt(1)
	v_cmp_gt_u32_e64 s[20:21], v60, v79
	v_addc_co_u32_e64 v95, s[30:31], 0, v95, s[24:25]
	v_cmp_gt_u32_e64 s[22:23], v61, v79
	v_addc_co_u32_e64 v95, s[30:31], 0, v95, s[26:27]
	v_cmp_gt_u32_e64 s[24:25], v62, v79
	v_addc_co_u32_e64 v95, s[30:31], 0, v95, s[20:21]
	v_cmp_gt_u32_e64 s[26:27], v63, v79
	v_addc_co_u32_e64 v95, s[30:31], 0, v95, s[22:23]
	s_waitcnt lgkmcnt(0)
	v_cmp_gt_u32_e64 s[20:21], v96, v79
	v_addc_co_u32_e64 v95, s[30:31], 0, v95, s[24:25]
	v_cmp_gt_u32_e64 s[22:23], v97, v79
	v_addc_co_u32_e64 v95, s[30:31], 0, v95, s[26:27]
	v_addc_co_u32_e64 v95, s[30:31], 0, v95, s[20:21]
	s_nop 1
	v_addc_co_u32_e64 v95, s[30:31], 0, v95, s[22:23]
	v_cmp_gt_u32_e64 s[20:21], 16, v88
	v_cmp_eq_u32_e64 s[22:23], 0, v88
	v_lshl_add_u32 v88, v88, 4, v174
	s_and_b64 s[20:21], s[20:21], s[34:35]
	s_ff1_i32_b64 s24, s[22:23]
	v_add_u32_e32 v88, 0, v88
	v_readlane_b32 s25, v64, s24
	v_cndmask_b32_e64 v88, v101, v88, s[20:21]
	s_nop 0
	v_subrev_f32_e32 v72, s25, v64
	v_mul_f32_e32 v72, 0x3fb8aa3b, v72
	v_exp_f32_e32 v72, v72
	s_nop 0
	v_cndmask_b32_e64 v72, 0, v72, s[20:21]
	v_cmp_gt_u32_e64 s[20:21], 16, v89
	v_cmp_eq_u32_e64 s[22:23], 0, v89
	v_lshl_add_u32 v89, v89, 4, v174
	s_and_b64 s[20:21], s[20:21], s[34:35]
	s_ff1_i32_b64 s24, s[22:23]
	v_add_u32_e32 v89, 256, v89
	v_readlane_b32 s25, v65, s24
	v_cndmask_b32_e64 v89, v101, v89, s[20:21]
	s_nop 0
	v_subrev_f32_e32 v73, s25, v65
	v_mul_f32_e32 v73, 0x3fb8aa3b, v73
	v_exp_f32_e32 v73, v73
	s_nop 0
	v_cndmask_b32_e64 v73, 0, v73, s[20:21]
	v_cmp_gt_u32_e64 s[20:21], 16, v90
	v_cmp_eq_u32_e64 s[22:23], 0, v90
	v_lshl_add_u32 v90, v90, 4, v174
	s_and_b64 s[20:21], s[20:21], s[34:35]
	s_ff1_i32_b64 s24, s[22:23]
	v_add_u32_e32 v90, 512, v90
	v_readlane_b32 s25, v66, s24
	v_cndmask_b32_e64 v90, v101, v90, s[20:21]
	s_nop 0
	v_subrev_f32_e32 v74, s25, v66
	v_mul_f32_e32 v74, 0x3fb8aa3b, v74
	v_exp_f32_e32 v74, v74
	s_nop 0
	v_cndmask_b32_e64 v74, 0, v74, s[20:21]
	v_cmp_gt_u32_e64 s[20:21], 16, v91
	v_cmp_eq_u32_e64 s[22:23], 0, v91
	v_lshl_add_u32 v91, v91, 4, v174
	s_and_b64 s[20:21], s[20:21], s[34:35]
	s_ff1_i32_b64 s24, s[22:23]
	v_add_u32_e32 v91, 768, v91
	v_readlane_b32 s25, v67, s24
	v_cndmask_b32_e64 v91, v101, v91, s[20:21]
	s_nop 0
	v_subrev_f32_e32 v75, s25, v67
	v_mul_f32_e32 v75, 0x3fb8aa3b, v75
	v_exp_f32_e32 v75, v75
	s_nop 0
	v_cndmask_b32_e64 v75, 0, v75, s[20:21]
	v_cmp_gt_u32_e64 s[20:21], 16, v92
	v_cmp_eq_u32_e64 s[22:23], 0, v92
	v_lshl_add_u32 v92, v92, 4, v174
	s_and_b64 s[20:21], s[20:21], s[34:35]
	s_ff1_i32_b64 s24, s[22:23]
	v_add_u32_e32 v92, 1024, v92
	v_readlane_b32 s25, v68, s24
	v_cndmask_b32_e64 v92, v101, v92, s[20:21]
	s_nop 0
	v_subrev_f32_e32 v76, s25, v68
	v_mul_f32_e32 v76, 0x3fb8aa3b, v76
	v_exp_f32_e32 v76, v76
	s_nop 0
	v_cndmask_b32_e64 v76, 0, v76, s[20:21]
	v_cmp_gt_u32_e64 s[20:21], 16, v93
	v_cmp_eq_u32_e64 s[22:23], 0, v93
	v_lshl_add_u32 v93, v93, 4, v174
	s_and_b64 s[20:21], s[20:21], s[34:35]
	s_ff1_i32_b64 s24, s[22:23]
	v_add_u32_e32 v93, 1280, v93
	v_readlane_b32 s25, v69, s24
	v_cndmask_b32_e64 v93, v101, v93, s[20:21]
	s_nop 0
	v_subrev_f32_e32 v77, s25, v69
	v_mul_f32_e32 v77, 0x3fb8aa3b, v77
	v_exp_f32_e32 v77, v77
	s_nop 0
	v_cndmask_b32_e64 v77, 0, v77, s[20:21]
	v_cmp_gt_u32_e64 s[20:21], 16, v94
	v_cmp_eq_u32_e64 s[22:23], 0, v94
	v_lshl_add_u32 v94, v94, 4, v174
	s_and_b64 s[20:21], s[20:21], s[34:35]
	s_ff1_i32_b64 s24, s[22:23]
	v_add_u32_e32 v94, 1536, v94
	v_readlane_b32 s25, v70, s24
	v_cndmask_b32_e64 v94, v101, v94, s[20:21]
	s_nop 0
	v_subrev_f32_e32 v78, s25, v70
	v_mul_f32_e32 v78, 0x3fb8aa3b, v78
	v_exp_f32_e32 v78, v78
	s_nop 0
	v_cndmask_b32_e64 v78, 0, v78, s[20:21]
	v_cmp_gt_u32_e64 s[20:21], 16, v95
	v_cmp_eq_u32_e64 s[22:23], 0, v95
	v_lshl_add_u32 v95, v95, 4, v174
	s_and_b64 s[20:21], s[20:21], s[34:35]
	s_ff1_i32_b64 s24, s[22:23]
	v_add_u32_e32 v95, 1792, v95
	v_readlane_b32 s25, v71, s24
	v_cndmask_b32_e64 v95, v101, v95, s[20:21]
	s_nop 0
	v_subrev_f32_e32 v79, s25, v71
	v_mul_f32_e32 v79, 0x3fb8aa3b, v79
	v_exp_f32_e32 v79, v79
	s_nop 0
	v_cndmask_b32_e64 v79, 0, v79, s[20:21]
	v_mov_b32_e32 v96, v72
	v_mov_b32_e32 v97, v73
	v_mov_b32_e32 v98, v74
	v_mov_b32_e32 v99, v75
	v_mov_b32_e32 v60, v76
	v_mov_b32_e32 v61, v77
	v_mov_b32_e32 v62, v78
	v_mov_b32_e32 v63, v79
	v_add_f32_dpp v96, v96, v96 quad_perm:[1,0,3,2] row_mask:0xf bank_mask:0xf
	v_add_f32_dpp v97, v97, v97 quad_perm:[1,0,3,2] row_mask:0xf bank_mask:0xf
	v_add_f32_dpp v98, v98, v98 quad_perm:[1,0,3,2] row_mask:0xf bank_mask:0xf
	v_add_f32_dpp v99, v99, v99 quad_perm:[1,0,3,2] row_mask:0xf bank_mask:0xf
	v_add_f32_dpp v60, v60, v60 quad_perm:[1,0,3,2] row_mask:0xf bank_mask:0xf
	v_add_f32_dpp v61, v61, v61 quad_perm:[1,0,3,2] row_mask:0xf bank_mask:0xf
	v_add_f32_dpp v62, v62, v62 quad_perm:[1,0,3,2] row_mask:0xf bank_mask:0xf
	v_add_f32_dpp v63, v63, v63 quad_perm:[1,0,3,2] row_mask:0xf bank_mask:0xf
	v_add_f32_dpp v96, v96, v96 quad_perm:[2,3,0,1] row_mask:0xf bank_mask:0xf
	v_add_f32_dpp v97, v97, v97 quad_perm:[2,3,0,1] row_mask:0xf bank_mask:0xf
	v_add_f32_dpp v98, v98, v98 quad_perm:[2,3,0,1] row_mask:0xf bank_mask:0xf
	v_add_f32_dpp v99, v99, v99 quad_perm:[2,3,0,1] row_mask:0xf bank_mask:0xf
	v_add_f32_dpp v60, v60, v60 quad_perm:[2,3,0,1] row_mask:0xf bank_mask:0xf
	v_add_f32_dpp v61, v61, v61 quad_perm:[2,3,0,1] row_mask:0xf bank_mask:0xf
	v_add_f32_dpp v62, v62, v62 quad_perm:[2,3,0,1] row_mask:0xf bank_mask:0xf
	v_add_f32_dpp v63, v63, v63 quad_perm:[2,3,0,1] row_mask:0xf bank_mask:0xf
	v_add_f32_dpp v96, v96, v96 row_half_mirror row_mask:0xf bank_mask:0xf
	v_add_f32_dpp v97, v97, v97 row_half_mirror row_mask:0xf bank_mask:0xf
	v_add_f32_dpp v98, v98, v98 row_half_mirror row_mask:0xf bank_mask:0xf
	v_add_f32_dpp v99, v99, v99 row_half_mirror row_mask:0xf bank_mask:0xf
	v_add_f32_dpp v60, v60, v60 row_half_mirror row_mask:0xf bank_mask:0xf
	v_add_f32_dpp v61, v61, v61 row_half_mirror row_mask:0xf bank_mask:0xf
	v_add_f32_dpp v62, v62, v62 row_half_mirror row_mask:0xf bank_mask:0xf
	v_add_f32_dpp v63, v63, v63 row_half_mirror row_mask:0xf bank_mask:0xf
	v_add_f32_dpp v96, v96, v96 row_mirror row_mask:0xf bank_mask:0xf
	v_add_f32_dpp v97, v97, v97 row_mirror row_mask:0xf bank_mask:0xf
	v_add_f32_dpp v98, v98, v98 row_mirror row_mask:0xf bank_mask:0xf
	v_add_f32_dpp v99, v99, v99 row_mirror row_mask:0xf bank_mask:0xf
	v_add_f32_dpp v60, v60, v60 row_mirror row_mask:0xf bank_mask:0xf
	v_add_f32_dpp v61, v61, v61 row_mirror row_mask:0xf bank_mask:0xf
	v_add_f32_dpp v62, v62, v62 row_mirror row_mask:0xf bank_mask:0xf
	v_add_f32_dpp v63, v63, v63 row_mirror row_mask:0xf bank_mask:0xf
	v_mov_b32_e32 v64, v96
	v_mov_b32_e32 v65, v97
	v_mov_b32_e32 v66, v98
	v_mov_b32_e32 v67, v99
	v_mov_b32_e32 v68, v60
	v_mov_b32_e32 v69, v61
	v_mov_b32_e32 v70, v62
	v_mov_b32_e32 v71, v63
	v_permlane16_swap_b32_e32 v64, v96
	v_permlane16_swap_b32_e32 v65, v97
	v_permlane16_swap_b32_e32 v66, v98
	v_permlane16_swap_b32_e32 v67, v99
	v_permlane16_swap_b32_e32 v68, v60
	v_permlane16_swap_b32_e32 v69, v61
	v_permlane16_swap_b32_e32 v70, v62
	v_permlane16_swap_b32_e32 v71, v63
	v_add_f32_e32 v96, v96, v64
	v_add_f32_e32 v97, v97, v65
	v_add_f32_e32 v98, v98, v66
	v_add_f32_e32 v99, v99, v67
	v_add_f32_e32 v60, v60, v68
	v_add_f32_e32 v61, v61, v69
	v_add_f32_e32 v62, v62, v70
	v_add_f32_e32 v63, v63, v71
	v_mov_b32_e32 v64, v96
	v_mov_b32_e32 v65, v97
	v_mov_b32_e32 v66, v98
	v_mov_b32_e32 v67, v99
	v_mov_b32_e32 v68, v60
	v_mov_b32_e32 v69, v61
	v_mov_b32_e32 v70, v62
	v_mov_b32_e32 v71, v63
	v_permlane32_swap_b32_e32 v64, v96
	v_permlane32_swap_b32_e32 v65, v97
	v_permlane32_swap_b32_e32 v66, v98
	v_permlane32_swap_b32_e32 v67, v99
	v_permlane32_swap_b32_e32 v68, v60
	v_permlane32_swap_b32_e32 v69, v61
	v_permlane32_swap_b32_e32 v70, v62
	v_permlane32_swap_b32_e32 v71, v63
	v_add_f32_e32 v96, v96, v64
	v_add_f32_e32 v97, v97, v65
	v_add_f32_e32 v98, v98, v66
	v_add_f32_e32 v99, v99, v67
	v_add_f32_e32 v60, v60, v68
	v_add_f32_e32 v61, v61, v69
	v_add_f32_e32 v62, v62, v70
	v_add_f32_e32 v63, v63, v71
	v_rcp_f32_e32 v96, v96
	v_rcp_f32_e32 v97, v97
	v_rcp_f32_e32 v98, v98
	v_rcp_f32_e32 v99, v99
	v_rcp_f32_e32 v60, v60
	v_rcp_f32_e32 v61, v61
	v_rcp_f32_e32 v62, v62
	v_rcp_f32_e32 v63, v63
	v_mul_f32_e32 v72, v72, v96
	v_mul_f32_e32 v73, v73, v97
	v_mul_f32_e32 v74, v74, v98
	v_mul_f32_e32 v75, v75, v99
	v_mul_f32_e32 v76, v76, v60
	v_mul_f32_e32 v77, v77, v61
	v_mul_f32_e32 v78, v78, v62
	v_mul_f32_e32 v79, v79, v63
	ds_write2_b32 v88, v80, v72 offset1:1
	ds_write2_b32 v89, v81, v73 offset1:1
	ds_write2_b32 v90, v82, v74 offset1:1
	ds_write2_b32 v91, v83, v75 offset1:1
	ds_write2_b32 v92, v84, v76 offset1:1
	ds_write2_b32 v93, v85, v77 offset1:1
	ds_write2_b32 v94, v86, v78 offset1:1
	ds_write2_b32 v95, v87, v79 offset1:1
	s_waitcnt lgkmcnt(0)
